# P13->P14 panel wait deferred into the first P14 K loop (gate GEMM does not read y_n)
# baseline (speedup 1.0000x reference)
.LBB0_1049:
	s_cmp_lg_u32 s100, 1
	s_cbranch_scc1 .Ldw_skip_p7
	s_cmp_lg_u32 s69, 8
	s_cbranch_scc1 .Ldw_skip_p7
	s_mov_b32 s100, 0
	s_cmp_eq_u64 s[92:93], 0
	s_cbranch_scc1 .Ldw_skip_p7
	s_mov_b32 s99, 0x2b5d008
	v_mov_b32_e32 v216, s99
	s_mov_b32 s101, 0x100000

.LBB0_1690:
	s_or_b64 exec, exec, s[8:9]
	s_waitcnt lgkmcnt(0)
	v_mov_b32_e32 v2, v0
	s_barrier
	s_mov_b32 s100, 1
	s_load_dwordx4 s[12:15], s[96:97], 0xe0
	v_readlane_b32 s0, v254, 5
	v_mov_b32_e32 v6, v0
	v_readlane_b32 s1, v254, 6
	s_waitcnt lgkmcnt(0)
	s_add_u32 s3, s14, 0xae00000
	s_addc_u32 s4, s15, 0
	s_and_b64 vcc, exec, s[0:1]
	v_readfirstlane_b32 s0, v6
	s_cbranch_vccnz .LBB0_1692
	s_and_b32 s1, s83, 56
	s_ashr_i32 s5, s2, 5
	s_add_i32 s6, s1, s5
	s_ashr_i32 s7, s6, 31
	s_lshl_b64 s[8:9], s[6:7], 19
	s_add_u32 s60, s3, s8
	s_addc_u32 s61, s4, s9
	s_lshl_b32 s1, s2, 5
	s_and_b32 s83, s1, 0x300
	s_lshl_b32 s1, s83, 11
	s_add_u32 s1, s14, s1
	s_addc_u32 s5, s15, 0
	s_add_u32 s62, s1, 0xc00000
	s_addc_u32 s63, s5, 0
	s_lshl_b32 s1, s83, 2
	s_add_u32 s1, s14, s1
	s_addc_u32 s5, s15, 0
	s_add_u32 s56, s1, 0x2106000
	s_addc_u32 s57, s5, 0
	s_lshl_b32 s84, s6, 8
	s_branch .LBB0_1693

.LBB0_1706:
	s_cmp_lg_u32 s100, 1
	s_cbranch_scc1 .Ldw_skip_p14
	s_cmp_lg_u32 s86, 8
	s_cbranch_scc1 .Ldw_skip_p14
	s_mov_b32 s100, 0
	s_cmp_eq_u64 s[92:93], 0
	s_cbranch_scc1 .Ldw_skip_p14
	s_and_b32 s99, s2, 7
	s_lshl_b32 s99, s99, 3
	s_lshr_b32 s101, s2, 5
	s_add_i32 s99, s99, s101
	s_lshl_b32 s99, s99, 8
	s_add_i32 s99, s99, 0x2b5d004
	v_mov_b32_e32 v218, s99
	s_mov_b32 s101, 0x100000
.Ldw_poll_p14:
	global_load_dword v219, v218, s[88:89] sc1
	s_waitcnt vmcnt(0)
	v_readfirstlane_b32 s99, v219
	s_cmp_ge_u32 s99, 0x4
	s_cbranch_scc1 .Ldw_done_p14
	s_sleep 1
	s_sub_u32 s101, s101, 1
	s_cmp_lg_u32 s101, 0
	s_cbranch_scc1 .Ldw_poll_p14
.Ldw_done_p14:
	buffer_inv sc1
.Ldw_skip_p14:
	ds_read_b128 v[130:133], v213
	ds_read_b128 v[134:137], v213 offset:1024
	ds_read_b128 v[138:141], v213 offset:2048
	ds_read_b128 v[142:145], v213 offset:3072
	ds_read_b128 v[178:181], v215
	ds_read_b128 v[182:185], v215 offset:1024
	ds_read_b128 v[186:189], v215 offset:2048
	ds_read_b128 v[190:193], v215 offset:3072
	s_add_u32 s0, s60, 0xfffc0080
	s_addc_u32 s1, s61, -1
	s_cmp_eq_u32 s86, 12
	s_cselect_b32 s1, s9, s1
	s_cselect_b32 s0, s8, s0
	s_cselect_b32 s31, s59, s63
	s_cselect_b32 s30, s58, s62
	v_lshl_add_u64 v[252:253], s[60:61], 0, v[198:199]
	s_add_i32 m0, s6, 0xc000
	ds_read_b128 v[146:149], v214
	ds_read_b128 v[150:153], v214 offset:1024
	ds_read_b128 v[154:157], v214 offset:2048
	ds_read_b128 v[158:161], v214 offset:3072
	ds_read_b128 v[162:165], v214 offset:4096
	ds_read_b128 v[166:169], v214 offset:5120
	ds_read_b128 v[170:173], v214 offset:6144
	ds_read_b128 v[174:177], v214 offset:7168
	global_load_lds_dwordx4 v[252:253], off
	v_lshl_add_u64 v[252:253], v[252:253], 0, s[10:11]
	s_add_i32 m0, s6, 0xe000
	s_nop 0
	global_load_lds_dwordx4 v[252:253], off
	s_cmp_lg_u32 s98, 0
	s_cbranch_scc1 .Lsk1_p14
	s_waitcnt vmcnt(8)
